# HGRN intra-chunk A blocks reassigned among wave pairs so each SIMD gets at most 3 causal blocks (was 4/1 imbalance)
# speedup vs baseline: 1.0060x; 1.0057x over previous
; #define LAS __attribute__((address_space(3)))
; DI void hgrn_scan_phase(int wv, const P& p_, LAS unsigned char* lds, float* sumsq) {
;     ...
;       const int mt = wid >> 1, vt = wid & 1;
;       f32x4 oacc = (f32x4){0.f, 0.f, 0.f, 0.f}, a0 = oacc, a1 = oacc;
;       const int J0 = 2 * vt;
; #pragma unroll
;       for (int ks = 0; ks < 4; ++ks) {
;         const int kb = 32 * ks + 8 * fq, trow = 16 * mt + fr;
;         const bf16x8 qv = *(const LAS bf16x8*)(Q + trow * 136 + kb);
;         const f32x4 bc0 = *(const LAS f32x4*)(BC + trow * 132 + kb), bc1 = *(const LAS f32x4*)(BC + trow * 132 + kb + 4);
;         const f32x4 r0 = *(const LAS f32x4*)(BC + (16 * mt) * 132 + kb), r1 = *(const LAS f32x4*)(BC + (16 * mt) * 132 + kb + 4);
;         u32x4 ai, aq;
; #pragma unroll
;         for (int j = 0; j < 4; ++j) {
;           const float q0 = bf2f((bf16_t)qv[2 * j]), q1 = bf2f((bf16_t)qv[2 * j + 1]);
;           const float b0 = j < 2 ? bc0[2 * j] : bc1[2 * j - 4], b1 = j < 2 ? bc0[2 * j + 1] : bc1[2 * j - 3];
;           const float rr0 = j < 2 ? r0[2 * j] : r1[2 * j - 4], rr1 = j < 2 ? r0[2 * j + 1] : r1[2 * j - 3];
;           ai[j] = pk2(q0 * __builtin_amdgcn_exp2f(b0), q1 * __builtin_amdgcn_exp2f(b1)); aq[j] = pk2(q0 * __builtin_amdgcn_exp2f(b0 - rr0), q1 * __builtin_amdgcn_exp2f(b1 - rr1));
;         }
;         const bf16x8 sb = *(const LAS bf16x8*)(ST + (16 * vt + fr) * 136 + kb);
;         oacc = MFMA16(__builtin_bit_cast(bf16x8, ai), sb, oacc);
; #pragma unroll
;         for (int jj = 0; jj < 2; ++jj) {
;           const int J = J0 + jj; if (J > mt) continue;
;           const int srow = 16 * J + fr;
;           const bf16x8 kv = *(const LAS bf16x8*)(Kr + srow * 136 + kb);
;           const f32x4 c0 = *(const LAS f32x4*)(BC + srow * 132 + kb), c1 = *(const LAS f32x4*)(BC + srow * 132 + kb + 4);
;           u32x4 bk;
; #pragma unroll
;           for (int j = 0; j < 4; ++j) {
;             const float k0 = bf2f((bf16_t)kv[2 * j]), k1 = bf2f((bf16_t)kv[2 * j + 1]);
;             const float b0 = j < 2 ? c0[2 * j] : c1[2 * j - 4], b1 = j < 2 ? c0[2 * j + 1] : c1[2 * j - 3];
;             const float rr0 = j < 2 ? r0[2 * j] : r1[2 * j - 4], rr1 = j < 2 ? r0[2 * j + 1] : r1[2 * j - 3];
;             bk[j] = pk2(k0 * __builtin_amdgcn_exp2f(fminf(rr0 - b0, 115.f)), k1 * __builtin_amdgcn_exp2f(fminf(rr1 - b1, 115.f)));
;           }
.LBB0_430:
	s_mov_b64 s[22:23], 0
	v_readlane_b32 s0, v253, 16
	s_waitcnt vmcnt(4)
	v_mbcnt_lo_u32_b32 v0, -1, 0
	v_mbcnt_hi_u32_b32 v0, -1, v0
	v_readlane_b32 s1, v253, 17
	s_add_i32 s66, s33, -1
	v_add_u32_e32 v0, s69, v0
	s_andn2_b64 vcc, exec, s[0:1]
	s_cbranch_vccnz .LBB0_429
	s_cmp_eq_u32 s66, 0
	s_mov_b32 s0, 0x1f340000
	s_cselect_b32 s0, s0, 0x1f440000
	v_readlane_b32 s1, v255, 32
	s_add_u32 s67, s1, s0
	v_readlane_b32 s0, v255, 34
	v_readlane_b32 s4, v254, 27
	v_add_u32_e32 v4, 0x200, v0
	s_addc_u32 s79, s0, 0
	v_readlane_b32 s6, v254, 29
	v_readlane_b32 s7, v254, 30
	v_readlane_b32 s18, v254, 41
	s_movk_i32 s0, 0x880
	v_lshlrev_b32_e32 v5, 3, v0
	v_ashrrev_i32_e32 v82, 4, v4
	v_ashrrev_i32_e32 v4, 2, v0
	v_readlane_b32 s8, v254, 31
	v_readlane_b32 s9, v254, 32
	v_readlane_b32 s19, v254, 42
	s_add_u32 s24, s18, s22
	v_cmp_gt_i32_e64 s[6:7], s0, v0
	v_and_b32_e32 v78, 0x78, v5
	s_movk_i32 s0, 0x100
	v_and_b32_e32 v6, 24, v5
	v_ashrrev_i32_e32 v5, 31, v4
	v_readlane_b32 s10, v254, 33
	v_readlane_b32 s11, v254, 34
	s_addc_u32 s25, s19, s23
	v_cmp_gt_i32_e64 s[8:9], s0, v0
	s_movk_i32 s0, 0xff
	v_lshlrev_b64 v[8:9], 11, v[4:5]
	v_cmp_lt_i32_e64 s[10:11], s0, v0
	v_lshl_add_u64 v[10:11], s[24:25], 0, v[8:9]
	s_mov_b64 s[0:1], 0xf000000
	v_lshl_add_u64 v[86:87], v[10:11], 0, s[0:1]
	v_readlane_b32 s1, v254, 59
	v_ashrrev_i32_e32 v12, 7, v0
	v_readlane_b32 s5, v254, 28
	v_lshl_add_u32 v7, v4, 1, s1
	v_and_b32_e32 v4, 0x7f, v0
	v_and_b32_e32 v2, 15, v0
	v_lshlrev_b32_e32 v5, 1, v78
	v_readlane_b32 s0, v254, 58
	v_lshlrev_b32_e32 v11, 12, v12
	v_lshlrev_b32_e32 v13, 1, v4
	v_lshlrev_b32_e32 v15, 4, v12
	v_readlane_b32 s4, v254, 61
	v_ashrrev_i32_e32 v3, 6, v0
	s_mov_b32 s98, 0x20201020
	s_mov_b32 s99, 0x31133231
	v_lshlrev_b32_e32 v216, 2, v3
	v_lshrrev_b32_e64 v217, v216, s99
	v_lshrrev_b32_e64 v216, v216, s98
	v_and_b32_e32 v216, 3, v216
	v_and_b32_e32 v217, 3, v217
	v_add_u32_e32 v10, 0, v5
	v_add_u32_e32 v5, s0, v5
	v_add3_u32 v79, s0, v11, v13
	v_readlane_b32 s0, v254, 60
	v_lshlrev_b32_e32 v11, 2, v4
	v_mov_b32_e32 v16, s4
	v_readlane_b32 s5, v254, 62
	v_or_b32_e32 v20, v15, v2
	s_movk_i32 s27, 0x110
	v_bfe_u32 v1, v0, 4, 2
	v_add_u32_e32 v119, s0, v11
	v_add_u32_e32 v120, 0, v11
	v_mad_u32_u24 v16, v4, s90, v16
	v_add_u32_e32 v121, s5, v11
	v_and_b32_e32 v11, 1, v3
	v_mul_lo_u32 v4, v20, s27
	s_add_u32 s28, s24, 0x7000000
	v_add_u32_e32 v21, 0, v4
	v_lshlrev_b32_e32 v22, 8, v20
	v_lshlrev_b32_e32 v4, 4, v11
	v_mul_lo_u32 v20, v20, s90
	v_lshlrev_b32_e32 v26, 4, v1
	v_readlane_b32 s38, v255, 0
	s_addc_u32 s29, s25, 0
	v_or_b32_e32 v23, v4, v2
	v_add3_u32 v123, s38, v20, v26
	v_add_u32_e32 v20, s1, v26
	s_add_u32 s30, s24, 0xb000000
	v_lshlrev_b32_e32 v14, 2, v0
	v_mul_u32_u24_e32 v24, 0x110, v23
	v_mad_u32_u24 v124, v23, s90, v20
	v_and_b32_e32 v23, 0xffffffc0, v0
	s_addc_u32 s31, s25, 0
	v_ashrrev_i32_e32 v76, 4, v0
	v_add_u32_e32 v118, s0, v14
	v_lshlrev_b32_e32 v18, 1, v11
	s_movk_i32 s0, 0x2100
	v_lshl_or_b32 v25, v1, 2, v15
	v_add3_u32 v125, s5, v23, v26
	v_lshl_or_b32 v23, v3, 4, v2
	v_lshl_or_b32 v28, v216, 4, v2
	s_add_u32 s34, s24, 0x17000000
	v_mul_lo_u32 v122, v12, s0
	v_mul_lo_u32 v23, v23, s90
	v_mad_u64_u32 v[88:89], s[0:1], v76, s27, v[10:11]
	v_mad_u64_u32 v[90:91], s[0:1], v82, s27, v[10:11]
	v_cmp_gt_i32_e32 vcc, v216, v12
	v_cmp_gt_i32_e64 s[20:21], v28, v25
	v_or_b32_e32 v10, 1, v25
	s_addc_u32 s35, s25, 0
	v_add3_u32 v126, s4, v23, v26
	s_or_b64 s[4:5], vcc, s[20:21]
	v_cmp_gt_i32_e64 s[20:21], v28, v10
	v_or_b32_e32 v11, 2, v25
	s_or_b64 s[68:69], vcc, s[20:21]
	v_cmp_gt_i32_e64 s[20:21], v28, v11
	v_or_b32_e32 v89, 3, v25
	v_lshl_or_b32 v29, v217, 4, v2
	s_or_b64 s[72:73], vcc, s[20:21]
	v_cmp_gt_i32_e64 s[20:21], v28, v89
	v_readlane_b32 s12, v254, 35
	v_readlane_b32 s13, v254, 36
	v_lshlrev_b32_e32 v19, 3, v1
	v_cmp_gt_i32_e64 s[0:1], v217, v12
	s_or_b64 s[74:75], vcc, s[20:21]
	v_cmp_gt_i32_e32 vcc, v29, v25
	s_movk_i32 s36, 0x90
	s_movk_i32 s26, 0x1100
	v_lshlrev_b32_e32 v1, 5, v1
	v_cmp_gt_u32_e64 s[12:13], s96, v0
	s_or_b64 s[62:63], s[0:1], vcc
	v_cmp_gt_i32_e32 vcc, v29, v10
	v_mul_lo_u32 v30, v12, s26
	v_or_b32_e32 v10, 1, v15
	s_movk_i32 s26, 0x210
	v_add3_u32 v127, v21, v22, v1
	v_add3_u32 v128, 0, v122, v1
	v_mul_lo_u32 v25, v25, s36
	v_lshlrev_b32_e32 v1, 1, v29
	v_add_u32_e32 v134, 0xfffffe00, v0
	v_and_b32_e32 v0, 3, v0
	v_lshl_add_u64 v[8:9], s[22:23], 0, v[8:9]
	v_mul_lo_u32 v15, v10, s26
	v_mul_lo_u32 v31, v10, s27
	v_add3_u32 v130, s38, v25, v1
	v_lshlrev_b32_e32 v0, 4, v0
	v_mov_b32_e32 v1, v32
	v_readlane_b32 s26, v254, 14
	v_lshl_add_u64 v[0:1], v[8:9], 0, v[0:1]
	v_readlane_b32 s27, v254, 15
	v_lshlrev_b32_e32 v3, 5, v3
	v_readlane_b32 s37, v254, 63
	s_or_b64 s[82:83], s[0:1], vcc
	v_cmp_gt_i32_e32 vcc, v29, v11
	v_add_u32_e32 v91, v21, v26
	v_add_u32_e32 v21, 0, v26
	v_lshlrev_b32_e32 v10, 4, v2
	v_mov_b32_e32 v11, v32
	v_lshl_add_u64 v[94:95], s[26:27], 0, v[0:1]
	v_readlane_b32 s26, v252, 14
	v_readlane_b32 s14, v254, 37
	v_readlane_b32 s15, v254, 38
	v_readlane_b32 s16, v254, 39
	v_readlane_b32 s17, v254, 40
	v_ashrrev_i32_e32 v77, 31, v76
	v_ashrrev_i32_e32 v83, 31, v82
	v_sub_u32_e32 v13, v120, v13
	v_lshlrev_b32_e32 v17, 5, v12
	v_add3_u32 v3, s37, v3, v19
	v_lshlrev_b32_e32 v19, 8, v76
	v_lshlrev_b32_e32 v23, 8, v82
	v_mul_u32_u24_e32 v27, 0x90, v6
	s_or_b64 s[90:91], s[0:1], vcc
	v_cmp_gt_i32_e32 vcc, v29, v89
	v_add3_u32 v129, s37, v24, v26
	v_add_u32_e32 v22, v21, v26
	v_lshl_add_u64 v[92:93], s[24:25], 0, v[10:11]
	v_mul_u32_u24_e32 v10, 0x110, v28
	v_mul_u32_u24_e32 v11, 0x210, v28
	v_lshl_add_u32 v24, v28, 1, s38
	v_mul_u32_u24_e32 v26, 0x90, v2
	v_mul_u32_u24_e32 v28, 0x110, v2
	v_readlane_b32 s27, v252, 15
	v_lshlrev_b64 v[80:81], 10, v[76:77]
	v_lshlrev_b64 v[84:85], 10, v[82:83]
	v_cmp_eq_u32_e64 s[14:15], 0, v2
	v_cmp_lt_i32_e64 s[16:17], 0, v12
	v_cmp_lt_i32_e64 s[18:19], 1, v12
	s_or_b64 s[0:1], s[0:1], vcc
	v_cmp_lt_i32_e64 s[20:21], 2, v12
	v_cmp_lt_i32_e64 s[22:23], 3, v12
	v_cmp_le_i32_e64 s[24:25], v216, v12
	v_add_u32_e32 v131, 0x90, v130
	v_add_u32_e32 v132, 0x120, v130
	v_add_u32_e32 v133, 0x1b0, v130
	v_add_u32_e32 v135, s37, v14
	v_lshlrev_b32_e32 v96, 1, v6
	s_waitcnt vmcnt(9)
	v_lshlrev_b32_e32 v98, 1, v4
	v_lshlrev_b32_e32 v100, 1, v2
	v_add_u32_e32 v136, v5, v19
	v_add_u32_e32 v137, v5, v23
	v_add_u32_e32 v138, v7, v27
	v_add_u32_e32 v139, v13, v30
	v_add_u32_e32 v140, v120, v15
	v_add_u32_e32 v141, v13, v31
	v_add_u32_e32 v142, v16, v17
	v_add_u32_e32 v143, v24, v25
	v_add_u32_e32 v144, v20, v26
	v_add_u32_e32 v145, v3, v28
	v_add_u32_e32 v146, v21, v10
	v_add_u32_e32 v147, v22, v11
	v_mul_u32_u24_e32 v218, 0x110, v29
	v_mul_u32_u24_e32 v219, 0x210, v29
	v_add_u32_e32 v218, 0xffffef00, v218
	v_add_u32_e32 v219, 0xffffdf00, v219
	v_add_u32_e32 v218, v21, v218
	v_add_u32_e32 v219, v22, v219
	v_readlane_b32 s54, v254, 12
	s_mov_b32 s57, s26
	v_cmp_le_i32_e64 s[26:27], v217, v12
	s_branch .LBB0_433

; #define LAS __attribute__((address_space(3)))
; DI unsigned pk2(float a, float b) { typedef __bf16 bf2 __attribute__((ext_vector_type(2))); bf2 v; v[0] = (__bf16)a; v[1] = (__bf16)b; return __builtin_bit_cast(unsigned, v); }
; DI float bf2f(bf16_t v) { return __uint_as_float(((unsigned)v) << 16); }
; #define MFMA16(a, b, c) __builtin_amdgcn_mfma_f32_16x16x32_bf16((a), (b), (c), 0, 0, 0)
; DI void hgrn_scan_phase(int wv, const P& p_, LAS unsigned char* lds, float* sumsq) {
;     ...
;         for (int jj = 0; jj < 2; ++jj) {
;           const int J = J0 + jj; if (J > mt) continue;
;           const int srow = 16 * J + fr;
;           const bf16x8 kv = *(const LAS bf16x8*)(Kr + srow * 136 + kb);
;           const f32x4 c0 = *(const LAS f32x4*)(BC + srow * 132 + kb), c1 = *(const LAS f32x4*)(BC + srow * 132 + kb + 4);
;           u32x4 bk;
; #pragma unroll
;           for (int j = 0; j < 4; ++j) {
;             const float k0 = bf2f((bf16_t)kv[2 * j]), k1 = bf2f((bf16_t)kv[2 * j + 1]);
;             const float b0 = j < 2 ? c0[2 * j] : c1[2 * j - 4], b1 = j < 2 ? c0[2 * j + 1] : c1[2 * j - 3];
;             const float rr0 = j < 2 ? r0[2 * j] : r1[2 * j - 4], rr1 = j < 2 ? r0[2 * j + 1] : r1[2 * j - 3];
;             bk[j] = pk2(k0 * __builtin_amdgcn_exp2f(fminf(rr0 - b0, 115.f)), k1 * __builtin_amdgcn_exp2f(fminf(rr1 - b1, 115.f)));
;           }
;           if (jj == 0) a0 = MFMA16(__builtin_bit_cast(bf16x8, aq), __builtin_bit_cast(bf16x8, bk), a0);
;           else a1 = MFMA16(__builtin_bit_cast(bf16x8, aq), __builtin_bit_cast(bf16x8, bk), a1);
.LBB0_452:
	s_or_b64 exec, exec, vcc
	v_mov_b64_e32 v[46:47], v[34:35]
	v_mov_b64_e32 v[44:45], v[32:33]
	s_and_saveexec_b64 vcc, s[26:27]
	s_cbranch_execz .LBB0_454
	ds_read_b128 v[44:47], v219 offset:43264
	ds_read_b128 v[148:151], v218 offset:21760
	ds_read_b128 v[152:155], v219 offset:43280
	s_waitcnt lgkmcnt(2)
	v_sub_f32_e32 v33, v64, v44
	v_sub_f32_e32 v34, v65, v45
	v_min_f32_e32 v33, 0x42e60000, v33
	v_min_f32_e32 v35, 0x42e60000, v34
	v_exp_f32_e32 v34, v33
	v_sub_f32_e32 v33, v66, v46
	v_min_f32_e32 v33, 0x42e60000, v33
	v_exp_f32_e32 v35, v35
	v_exp_f32_e32 v46, v33
	v_sub_f32_e32 v33, v67, v47
	v_min_f32_e32 v33, 0x42e60000, v33
	v_exp_f32_e32 v47, v33
	s_waitcnt lgkmcnt(1)
	v_and_b32_e32 v45, 0xffff0000, v148
	v_lshlrev_b32_e32 v44, 16, v148
	v_pk_mul_f32 v[34:35], v[34:35], v[44:45]
	s_waitcnt lgkmcnt(0)
	v_sub_f32_e32 v33, v56, v152
	v_cvt_pk_bf16_f32 v44, v34, v35
	v_and_b32_e32 v35, 0xffff0000, v149
	v_lshlrev_b32_e32 v34, 16, v149
	v_min_f32_e32 v33, 0x42e60000, v33
	v_pk_mul_f32 v[34:35], v[46:47], v[34:35]
	v_exp_f32_e32 v46, v33
	v_sub_f32_e32 v33, v57, v153
	v_min_f32_e32 v33, 0x42e60000, v33
	v_exp_f32_e32 v47, v33
	v_sub_f32_e32 v33, v58, v154
	v_min_f32_e32 v33, 0x42e60000, v33
	v_exp_f32_e32 v56, v33
	v_sub_f32_e32 v33, v59, v155
	v_min_f32_e32 v33, 0x42e60000, v33
	v_exp_f32_e32 v57, v33
	v_cvt_pk_bf16_f32 v45, v34, v35
	v_and_b32_e32 v35, 0xffff0000, v150
	v_lshlrev_b32_e32 v34, 16, v150
	v_pk_mul_f32 v[34:35], v[46:47], v[34:35]
	s_nop 0
	v_cvt_pk_bf16_f32 v46, v34, v35
	v_and_b32_e32 v35, 0xffff0000, v151
	v_lshlrev_b32_e32 v34, 16, v151
	v_pk_mul_f32 v[34:35], v[56:57], v[34:35]
	s_nop 0
	v_cvt_pk_bf16_f32 v47, v34, v35
	s_nop 1
	v_mfma_f32_16x16x32_bf16 v[44:47], v[60:63], v[44:47], 0

; #define LAS __attribute__((address_space(3)))
; DI unsigned pk2(float a, float b) { typedef __bf16 bf2 __attribute__((ext_vector_type(2))); bf2 v; v[0] = (__bf16)a; v[1] = (__bf16)b; return __builtin_bit_cast(unsigned, v); }
; DI float bf2f(bf16_t v) { return __uint_as_float(((unsigned)v) << 16); }
; #define MFMA16(a, b, c) __builtin_amdgcn_mfma_f32_16x16x32_bf16((a), (b), (c), 0, 0, 0)
; DI void hgrn_scan_phase(int wv, const P& p_, LAS unsigned char* lds, float* sumsq) {
;     ...
;         for (int jj = 0; jj < 2; ++jj) {
;           const int J = J0 + jj; if (J > mt) continue;
;           const int srow = 16 * J + fr;
;           const bf16x8 kv = *(const LAS bf16x8*)(Kr + srow * 136 + kb);
;           const f32x4 c0 = *(const LAS f32x4*)(BC + srow * 132 + kb), c1 = *(const LAS f32x4*)(BC + srow * 132 + kb + 4);
;           u32x4 bk;
; #pragma unroll
;           for (int j = 0; j < 4; ++j) {
;             const float k0 = bf2f((bf16_t)kv[2 * j]), k1 = bf2f((bf16_t)kv[2 * j + 1]);
;             const float b0 = j < 2 ? c0[2 * j] : c1[2 * j - 4], b1 = j < 2 ? c0[2 * j + 1] : c1[2 * j - 3];
;             const float rr0 = j < 2 ? r0[2 * j] : r1[2 * j - 4], rr1 = j < 2 ? r0[2 * j + 1] : r1[2 * j - 3];
;             bk[j] = pk2(k0 * __builtin_amdgcn_exp2f(fminf(rr0 - b0, 115.f)), k1 * __builtin_amdgcn_exp2f(fminf(rr1 - b1, 115.f)));
;           }
;           if (jj == 0) a0 = MFMA16(__builtin_bit_cast(bf16x8, aq), __builtin_bit_cast(bf16x8, bk), a0);
;           else a1 = MFMA16(__builtin_bit_cast(bf16x8, aq), __builtin_bit_cast(bf16x8, bk), a1);
.LBB0_456:
	s_or_b64 exec, exec, vcc
	s_and_saveexec_b64 vcc, s[26:27]
	s_cbranch_execz .LBB0_458
	ds_read_b128 v[148:151], v219 offset:43392
	ds_read_b128 v[152:155], v218 offset:21824
	ds_read_b128 v[156:159], v219 offset:43408
	s_waitcnt lgkmcnt(2)
	v_sub_f32_e32 v33, v68, v148
	v_sub_f32_e32 v68, v69, v149
	v_min_f32_e32 v33, 0x42e60000, v33
	v_min_f32_e32 v69, 0x42e60000, v68
	v_exp_f32_e32 v68, v33
	v_sub_f32_e32 v33, v70, v150
	v_min_f32_e32 v33, 0x42e60000, v33
	v_exp_f32_e32 v70, v33
	v_sub_f32_e32 v33, v71, v151
	v_min_f32_e32 v33, 0x42e60000, v33
	v_exp_f32_e32 v71, v33
	s_waitcnt lgkmcnt(0)
	v_sub_f32_e32 v33, v60, v156
	v_min_f32_e32 v33, 0x42e60000, v33
	v_exp_f32_e32 v60, v33
	v_sub_f32_e32 v33, v61, v157
	v_exp_f32_e32 v69, v69
	v_min_f32_e32 v33, 0x42e60000, v33
	v_exp_f32_e32 v61, v33
	v_sub_f32_e32 v33, v62, v158
	v_min_f32_e32 v33, 0x42e60000, v33
	v_and_b32_e32 v149, 0xffff0000, v152
	v_lshlrev_b32_e32 v148, 16, v152
	v_exp_f32_e32 v62, v33
	v_sub_f32_e32 v33, v63, v159
	v_pk_mul_f32 v[68:69], v[68:69], v[148:149]
	v_and_b32_e32 v149, 0xffff0000, v153
	v_lshlrev_b32_e32 v148, 16, v153
	v_min_f32_e32 v33, 0x42e60000, v33
	v_pk_mul_f32 v[70:71], v[70:71], v[148:149]
	v_exp_f32_e32 v63, v33
	v_cvt_pk_bf16_f32 v68, v68, v69
	v_cvt_pk_bf16_f32 v69, v70, v71
	v_and_b32_e32 v71, 0xffff0000, v154
	v_lshlrev_b32_e32 v70, 16, v154
	v_pk_mul_f32 v[60:61], v[60:61], v[70:71]
	s_nop 0
	v_cvt_pk_bf16_f32 v70, v60, v61
	v_and_b32_e32 v61, 0xffff0000, v155
	v_lshlrev_b32_e32 v60, 16, v155
	v_pk_mul_f32 v[60:61], v[62:63], v[60:61]
	s_nop 0
	v_cvt_pk_bf16_f32 v71, v60, v61
	s_nop 1
	v_mfma_f32_16x16x32_bf16 v[44:47], v[64:67], v[68:71], v[44:47]

; #define LAS __attribute__((address_space(3)))
; DI unsigned pk2(float a, float b) { typedef __bf16 bf2 __attribute__((ext_vector_type(2))); bf2 v; v[0] = (__bf16)a; v[1] = (__bf16)b; return __builtin_bit_cast(unsigned, v); }
; DI float bf2f(bf16_t v) { return __uint_as_float(((unsigned)v) << 16); }
; #define MFMA16(a, b, c) __builtin_amdgcn_mfma_f32_16x16x32_bf16((a), (b), (c), 0, 0, 0)
; DI void hgrn_scan_phase(int wv, const P& p_, LAS unsigned char* lds, float* sumsq) {
;     ...
;         for (int jj = 0; jj < 2; ++jj) {
;           const int J = J0 + jj; if (J > mt) continue;
;           const int srow = 16 * J + fr;
;           const bf16x8 kv = *(const LAS bf16x8*)(Kr + srow * 136 + kb);
;           const f32x4 c0 = *(const LAS f32x4*)(BC + srow * 132 + kb), c1 = *(const LAS f32x4*)(BC + srow * 132 + kb + 4);
;           u32x4 bk;
; #pragma unroll
;           for (int j = 0; j < 4; ++j) {
;             const float k0 = bf2f((bf16_t)kv[2 * j]), k1 = bf2f((bf16_t)kv[2 * j + 1]);
;             const float b0 = j < 2 ? c0[2 * j] : c1[2 * j - 4], b1 = j < 2 ? c0[2 * j + 1] : c1[2 * j - 3];
;             const float rr0 = j < 2 ? r0[2 * j] : r1[2 * j - 4], rr1 = j < 2 ? r0[2 * j + 1] : r1[2 * j - 3];
;             bk[j] = pk2(k0 * __builtin_amdgcn_exp2f(fminf(rr0 - b0, 115.f)), k1 * __builtin_amdgcn_exp2f(fminf(rr1 - b1, 115.f)));
;           }
;           if (jj == 0) a0 = MFMA16(__builtin_bit_cast(bf16x8, aq), __builtin_bit_cast(bf16x8, bk), a0);
;           else a1 = MFMA16(__builtin_bit_cast(bf16x8, aq), __builtin_bit_cast(bf16x8, bk), a1);
.LBB0_460:
	s_or_b64 exec, exec, vcc
	s_and_saveexec_b64 vcc, s[26:27]
	s_cbranch_execz .LBB0_462
	ds_read_b128 v[148:151], v219 offset:43520
	ds_read_b128 v[152:155], v218 offset:21888
	ds_read_b128 v[156:159], v219 offset:43536
	s_waitcnt lgkmcnt(2)
	v_sub_f32_e32 v33, v68, v148
	v_sub_f32_e32 v68, v69, v149
	v_min_f32_e32 v33, 0x42e60000, v33
	v_min_f32_e32 v69, 0x42e60000, v68
	v_exp_f32_e32 v68, v33
	v_sub_f32_e32 v33, v70, v150
	v_min_f32_e32 v33, 0x42e60000, v33
	v_exp_f32_e32 v70, v33
	v_sub_f32_e32 v33, v71, v151
	v_min_f32_e32 v33, 0x42e60000, v33
	v_exp_f32_e32 v71, v33
	s_waitcnt lgkmcnt(0)
	v_sub_f32_e32 v33, v60, v156
	v_min_f32_e32 v33, 0x42e60000, v33
	v_exp_f32_e32 v60, v33
	v_sub_f32_e32 v33, v61, v157
	v_exp_f32_e32 v69, v69
	v_min_f32_e32 v33, 0x42e60000, v33
	v_exp_f32_e32 v61, v33
	v_sub_f32_e32 v33, v62, v158
	v_min_f32_e32 v33, 0x42e60000, v33
	v_and_b32_e32 v149, 0xffff0000, v152
	v_lshlrev_b32_e32 v148, 16, v152
	v_exp_f32_e32 v62, v33
	v_sub_f32_e32 v33, v63, v159
	v_pk_mul_f32 v[68:69], v[68:69], v[148:149]
	v_and_b32_e32 v149, 0xffff0000, v153
	v_lshlrev_b32_e32 v148, 16, v153
	v_min_f32_e32 v33, 0x42e60000, v33
	v_pk_mul_f32 v[70:71], v[70:71], v[148:149]
	v_exp_f32_e32 v63, v33
	v_cvt_pk_bf16_f32 v68, v68, v69
	v_cvt_pk_bf16_f32 v69, v70, v71
	v_and_b32_e32 v71, 0xffff0000, v154
	v_lshlrev_b32_e32 v70, 16, v154
	v_pk_mul_f32 v[60:61], v[60:61], v[70:71]
	s_nop 0
	v_cvt_pk_bf16_f32 v70, v60, v61
	v_and_b32_e32 v61, 0xffff0000, v155
	v_lshlrev_b32_e32 v60, 16, v155
	v_pk_mul_f32 v[60:61], v[62:63], v[60:61]
	s_nop 0
	v_cvt_pk_bf16_f32 v71, v60, v61
	s_nop 1
	v_mfma_f32_16x16x32_bf16 v[44:47], v[64:67], v[68:71], v[44:47]

; #define LAS __attribute__((address_space(3)))
; DI unsigned pk2(float a, float b) { typedef __bf16 bf2 __attribute__((ext_vector_type(2))); bf2 v; v[0] = (__bf16)a; v[1] = (__bf16)b; return __builtin_bit_cast(unsigned, v); }
; DI float bf2f(bf16_t v) { return __uint_as_float(((unsigned)v) << 16); }
; #define MFMA16(a, b, c) __builtin_amdgcn_mfma_f32_16x16x32_bf16((a), (b), (c), 0, 0, 0)
; DI void hgrn_scan_phase(int wv, const P& p_, LAS unsigned char* lds, float* sumsq) {
;     ...
;         for (int jj = 0; jj < 2; ++jj) {
;           const int J = J0 + jj; if (J > mt) continue;
;           const int srow = 16 * J + fr;
;           const bf16x8 kv = *(const LAS bf16x8*)(Kr + srow * 136 + kb);
;           const f32x4 c0 = *(const LAS f32x4*)(BC + srow * 132 + kb), c1 = *(const LAS f32x4*)(BC + srow * 132 + kb + 4);
;           u32x4 bk;
; #pragma unroll
;           for (int j = 0; j < 4; ++j) {
;             const float k0 = bf2f((bf16_t)kv[2 * j]), k1 = bf2f((bf16_t)kv[2 * j + 1]);
;             const float b0 = j < 2 ? c0[2 * j] : c1[2 * j - 4], b1 = j < 2 ? c0[2 * j + 1] : c1[2 * j - 3];
;             const float rr0 = j < 2 ? r0[2 * j] : r1[2 * j - 4], rr1 = j < 2 ? r0[2 * j + 1] : r1[2 * j - 3];
;             bk[j] = pk2(k0 * __builtin_amdgcn_exp2f(fminf(rr0 - b0, 115.f)), k1 * __builtin_amdgcn_exp2f(fminf(rr1 - b1, 115.f)));
;           }
;           if (jj == 0) a0 = MFMA16(__builtin_bit_cast(bf16x8, aq), __builtin_bit_cast(bf16x8, bk), a0);
;           else a1 = MFMA16(__builtin_bit_cast(bf16x8, aq), __builtin_bit_cast(bf16x8, bk), a1);
.LBB0_464:
	s_or_b64 exec, exec, vcc
	s_and_saveexec_b64 vcc, s[26:27]
	s_cbranch_execz .LBB0_466
	ds_read_b128 v[148:151], v219 offset:43648
	ds_read_b128 v[152:155], v218 offset:21952
	ds_read_b128 v[156:159], v219 offset:43664
	s_waitcnt lgkmcnt(2)
	v_sub_f32_e32 v33, v68, v148
	v_sub_f32_e32 v68, v69, v149
	v_min_f32_e32 v33, 0x42e60000, v33
	v_min_f32_e32 v69, 0x42e60000, v68
	v_exp_f32_e32 v68, v33
	v_sub_f32_e32 v33, v70, v150
	v_min_f32_e32 v33, 0x42e60000, v33
	v_exp_f32_e32 v70, v33
	v_sub_f32_e32 v33, v71, v151
	v_min_f32_e32 v33, 0x42e60000, v33
	v_exp_f32_e32 v71, v33
	s_waitcnt lgkmcnt(0)
	v_sub_f32_e32 v33, v60, v156
	v_min_f32_e32 v33, 0x42e60000, v33
	v_exp_f32_e32 v60, v33
	v_sub_f32_e32 v33, v61, v157
	v_exp_f32_e32 v69, v69
	v_min_f32_e32 v33, 0x42e60000, v33
	v_exp_f32_e32 v61, v33
	v_sub_f32_e32 v33, v62, v158
	v_min_f32_e32 v33, 0x42e60000, v33
	v_and_b32_e32 v149, 0xffff0000, v152
	v_lshlrev_b32_e32 v148, 16, v152
	v_exp_f32_e32 v62, v33
	v_sub_f32_e32 v33, v63, v159
	v_pk_mul_f32 v[68:69], v[68:69], v[148:149]
	v_and_b32_e32 v149, 0xffff0000, v153
	v_lshlrev_b32_e32 v148, 16, v153
	v_min_f32_e32 v33, 0x42e60000, v33
	v_pk_mul_f32 v[70:71], v[70:71], v[148:149]
	v_exp_f32_e32 v63, v33
	v_cvt_pk_bf16_f32 v68, v68, v69
	v_cvt_pk_bf16_f32 v69, v70, v71
	v_and_b32_e32 v71, 0xffff0000, v154
	v_lshlrev_b32_e32 v70, 16, v154
	v_pk_mul_f32 v[60:61], v[60:61], v[70:71]
	s_nop 0
	v_cvt_pk_bf16_f32 v70, v60, v61
	v_and_b32_e32 v61, 0xffff0000, v155
	v_lshlrev_b32_e32 v60, 16, v155
	v_pk_mul_f32 v[60:61], v[62:63], v[60:61]
	s_nop 0
	v_cvt_pk_bf16_f32 v71, v60, v61
	s_nop 1
	v_mfma_f32_16x16x32_bf16 v[44:47], v[64:67], v[68:71], v[44:47]
